# first grid seam (after phase 0) now uses the same XCD-aware atomic barrier as the other 14 seams instead of cooperative-groups grid sync
# baseline (speedup 1.0000x reference)
; __device__ __forceinline__ unsigned xb_ld(unsigned* p)              { return __hip_atomic_load(p, __ATOMIC_RELAXED, __HIP_MEMORY_SCOPE_AGENT); }
; __device__ __forceinline__ unsigned xb_add(unsigned* p, unsigned v) { return __hip_atomic_fetch_add(p, v, __ATOMIC_RELAXED, __HIP_MEMORY_SCOPE_AGENT); }
; __device__ __forceinline__ void xcd_barrier_complete(unsigned* bar, unsigned x, unsigned& nloc, unsigned& nx) {
;     const unsigned G = gridDim.x * gridDim.y * gridDim.z;
;     unsigned sum, cnt, mine, sp = 0u;
;     for (;;) {
;         sum = 0u; cnt = 0u; mine = 0u;
; #pragma unroll
;         for (unsigned j = 0; j < 16; ++j) { const unsigned c = xb_ld(&bar[XB_XCNT(j)]); sum += c; cnt += (c > 0u) ? 1u : 0u; mine = (j == x) ? c : mine; }
;         if (sum == G) break;
; __device__ __forceinline__ void xcd_barrier(const XcdBarrier& b) {
;     asm volatile("s_waitcnt vmcnt(0)" ::: "memory");
;     __syncthreads();
;     if (threadIdx.x == 0) {
;         unsigned* bar = b.bar;
;         __builtin_amdgcn_s_waitcnt(0);
;         unsigned nloc = b.st[0], nx = b.st[1];
;         if (nloc == 0u) { xcd_barrier_complete(bar, b.x, nloc, nx); b.st[0] = nloc; b.st[1] = nx; }
;         const unsigned old = xb_add(&bar[XB_XSUB(b.x)], 1u);
;         const unsigned gen = old / nloc;
;         if (old + 1u == (gen + 1u) * nloc) {
.LBB0_105:
	s_or_b64 exec, exec, s[0:1]
	s_cmp_lt_i32 s59, 2
	s_waitcnt vmcnt(0) lgkmcnt(0)
	s_barrier
	s_cbranch_scc1 .LBB0_117
	s_waitcnt vmcnt(0)
	s_barrier
	s_and_saveexec_b64 s[0:1], s[10:11]
	s_cbranch_execz .Lmy_b0_203
	s_add_i32 s3, 0, 0x20000
	v_mov_b32_e32 v0, s3
	s_waitcnt vmcnt(0) expcnt(0) lgkmcnt(0)
	ds_read_b32 v2, v0
	s_add_i32 s3, 0, 0x20004
	v_mov_b32_e32 v0, s3
	ds_read_b32 v0, v0
	s_waitcnt lgkmcnt(1)
	v_cmp_ne_u32_e32 vcc, 0, v2
	s_cbranch_vccnz .Lmy_b0_167
	s_add_u32 s4, s56, 0x3fa00200
	s_addc_u32 s5, s57, 0
	s_add_u32 s6, s56, 0x3fa00400
	s_addc_u32 s7, s57, 0
	s_add_u32 s8, s56, 0x3fa00500
	s_addc_u32 s9, s57, 0
	s_add_u32 s16, s56, 0x3fa00600
	s_addc_u32 s17, s57, 0
	s_add_u32 s18, s56, 0x3fa00700
	s_addc_u32 s19, s57, 0
	s_add_u32 s26, s56, 0x3fa00800
	s_addc_u32 s27, s57, 0
	s_add_u32 s28, s56, 0x3fa00900
	s_addc_u32 s29, s57, 0
	s_add_u32 s30, s56, 0x3fa00a00
	s_addc_u32 s31, s57, 0
	s_add_u32 s38, s56, 0x3fa00b00
	s_addc_u32 s39, s57, 0
	s_add_u32 s60, s56, 0x3fa00c00
	s_addc_u32 s61, s57, 0
	s_add_u32 s64, s56, 0x3fa00d00
	s_addc_u32 s65, s57, 0
	s_add_u32 s66, s56, 0x3fa00e00
	s_addc_u32 s67, s57, 0
	s_add_u32 s68, s56, 0x3fa00f00
	s_addc_u32 s69, s57, 0
	s_add_u32 s70, s56, 0x3fa01000
	s_addc_u32 s71, s57, 0
	s_add_u32 s72, s56, 0x3fa01100
	s_addc_u32 s73, s57, 0
	s_add_u32 s74, s56, 0x3fa01200
	v_readlane_b32 s3, v255, 0
	s_addc_u32 s75, s57, 0
	s_mul_i32 s3, s97, s3
	s_add_u32 s76, s56, 0x3fa01300
	s_mul_i32 s3, s3, s96
	s_addc_u32 s77, s57, 0
	s_mov_b32 s84, 1
	v_mov_b32_e32 v16, 0
	s_branch .Lmy_b0_155

;     __device__ bool next(int i, Unit& u) const {
;         const long L = (long)i * G + c; if (L >= nwg) return false;
;         int wgid = (int)L; { const int q = nwg / NXCD, r = nwg % NXCD, xcd = wgid % NXCD, off = wgid / NXCD; wgid = (xcd < r ? xcd * (q + 1) : r * (q + 1) + (xcd - r) * q) + off; }
;         const int nig = WGM * nN, gid = wgid / nig, fm = gid * WGM, gsz = (nM - fm) < WGM ? (nM - fm) : WGM;
;         u.pm = fm + ((wgid % nig) % gsz); u.pn = (wgid % nig) / gsz; return true;
; template <class Epi>
; __device__ __forceinline__ void gemm_phase(LAS unsigned char* lds, const Gemm g, const StaticOrder& S, const Epi& E) {
;     const int tid = threadIdx.x, wid = __builtin_amdgcn_readfirstlane(tid >> 6), lane = tid & 63, wr = wid >> 2, wc = wid & 3, fr = lane & 15, fq = lane >> 4;
;     const int K = g.K, nt = K / BK;
;     unsigned voffA[2], voffB[2];
; #pragma unroll
;     for (int i = 0; i < 2; ++i) { int R, C; stage_rc(tid * 16 + i * 8192, R, C); const int Rb = Epi::PERM ? ((R & ~31) + perm32(R & 31)) : R;
;         voffA[i] = (unsigned)(R * g.lda + C) * 2u; voffB[i] = (unsigned)(Rb * g.ldb + C) * 2u; }
;     const size_t kstep = (size_t)(BK * 2);
;     const size_t hstepA = (size_t)HALF * g.lda * 2, hstepB = (size_t)HALF * g.ldb * 2;
;     const size_t tstepA = 2 * hstepA, tstepB = 2 * hstepB;
;     const unsigned ldsw = (unsigned)wid * 1024u;
;     const int aoff = lds_byte(wr * 64 + fr, fq * 8), boff = lds_byte(wc * 32 + fr, fq * 8);
;     ...
;     Unit cur, nxt; int ui = 0;
;     if (!S.next(0, cur)) return;
;     f32x4 acc[2][2][4][2];
; #pragma unroll
;     for (int a = 0; a < 2; ++a)
; #pragma unroll
;         for (int b = 0; b < 2; ++b)
; #pragma unroll
;             for (int m = 0; m < 4; ++m)
; #pragma unroll
;                 for (int n = 0; n < 2; ++n) acc[a][b][m][n] = (f32x4){0.f, 0.f, 0.f, 0.f};
;     bf16x8 At[4][2], B0[2][2], B1[2][2];
;     const char* cA = (const char*)g.A + (size_t)cur.pm * tstepA; const char* cB = (const char*)g.Bt + (size_t)cur.pn * tstepB;
;     PG8_STAGE(PG8_SB(0, 0), cB, voffB); PG8_STAGE(PG8_SA(0, 0), cA, voffA); PG8_STAGE(PG8_SB(0, 1), cB + hstepB, voffB); PG8_STAGE(PG8_SA(0, 1), cA + hstepA, voffA);
;     if (wr == 1) PG8_BAR;
;     PG8_WAIT_V(4); PG8_BAR;
;     PG8_STAGE(PG8_SB(1, 0), cB + kstep, voffB); PG8_STAGE(PG8_SA(1, 0), cA + kstep, voffA); PG8_STAGE(PG8_SB(1, 1), cB + hstepB + kstep, voffB);
.Lmy_b0_203:
	s_or_b64 exec, exec, s[0:1]
	s_waitcnt lgkmcnt(0)
	s_barrier
.LBB0_117:
	s_cmp_lt_i32 s58, 2
	s_cselect_b64 s[0:1], -1, 0
	s_cmp_gt_i32 s59, 1
	s_cselect_b64 s[4:5], -1, 0
	s_and_b64 s[0:1], s[0:1], s[4:5]
	s_andn2_b64 vcc, exec, s[0:1]
	s_cbranch_vccnz .LBB0_204
	s_cmpk_gt_i32 s2, 0x107f
	v_readfirstlane_b32 s3, v254
	s_cbranch_scc1 .LBB0_150
	v_lshrrev_b32_e32 v0, 5, v254
	v_lshrrev_b32_e32 v2, 1, v254
	v_and_b32_e32 v0, 4, v0
	v_bfe_u32 v1, v254, 2, 2
	v_and_b32_e32 v11, 24, v2
	v_or3_b32 v0, v0, v1, v11
	v_lshlrev_b32_e32 v1, 4, v254
	v_add_u32_e32 v8, 0x2000, v1
	v_lshrrev_b32_e32 v2, 7, v8
	s_movk_i32 s0, 0xe0
	v_and_b32_e32 v4, 32, v254
	v_and_or_b32 v3, v2, s0, v0
	v_bitop3_b32 v9, v1, v4, 48 bitop3:0x6c
	v_and_b32_e32 v10, 64, v254
	v_bfe_u32 v12, v254, 2, 4
	s_movk_i32 s0, 0xf0
	v_or_b32_e32 v1, v9, v10
	v_and_or_b32 v2, v2, s0, v12
	s_add_u32 s72, s56, 0x3800000
	v_lshl_or_b32 v130, v2, 12, v1
	v_lshrrev_b32_e32 v2, 3, v254
	s_movk_i32 s0, 0x60
	s_addc_u32 s73, s57, 0
	v_and_or_b32 v0, v2, s0, v0
	s_movk_i32 s0, 0x70
	s_ashr_i32 s75, s2, 31
	v_lshl_or_b32 v132, v0, 12, v1
	v_and_or_b32 v0, v2, s0, v12
	s_lshr_b32 s0, s75, 29
	s_add_i32 s0, s2, s0
	s_lshr_b32 s5, s3, 6
	s_ashr_i32 s1, s0, 3
	s_and_b32 s0, s0, -8
	s_lshr_b32 s26, s3, 8
	s_lshl_b32 s74, s5, 10
	s_sub_i32 s0, s2, s0
	s_cmp_lt_i32 s0, 0
	s_movk_i32 s76, 0x211
	s_cselect_b32 s4, s76, 0x210
	s_mul_i32 s0, s4, s0
	s_add_i32 s0, s0, s1
	s_mul_hi_i32 s1, s0, 0x3e0f83e1
	s_lshr_b32 s4, s1, 31
	s_ashr_i32 s1, s1, 6
	s_add_i32 s1, s1, s4
	s_lshl_b32 s6, s1, 3
	s_mulk_i32 s1, 0x108
	s_sub_i32 s0, s0, s1
	s_sext_i32_i16 s1, s0
	s_bfe_u32 s1, s1, 0x3001c
	s_add_i32 s1, s0, s1
	s_sext_i32_i16 s4, s1
	s_and_b32 s1, s1, 0xfff8
	s_sub_i32 s0, s0, s1
	s_sext_i32_i16 s0, s0
	s_lshr_b32 s4, s4, 3
	s_add_i32 s64, s6, s0
	s_ashr_i32 s65, s64, 31
	s_bfe_i64 s[6:7], s[4:5], 0x100000
	s_lshl_b64 s[0:1], s[64:65], 20
	s_lshl_b64 s[6:7], s[6:7], 20
	s_add_u32 s68, s56, s6
	s_addc_u32 s69, s57, s7
	s_add_i32 s77, s74, 0
	s_add_i32 m0, s77, 0x10000
	v_lshl_or_b32 v128, v3, 12, v1
	global_load_lds_dwordx4 v132, s[68:69]
	s_add_i32 m0, s77, 0x12000
	s_add_u32 s66, s72, s0
	v_lshl_or_b32 v134, v0, 12, v1
	global_load_lds_dwordx4 v128, s[68:69]
	s_addc_u32 s67, s73, s1
	s_mov_b32 m0, s77
	s_add_i32 s78, s77, 0x2000
	global_load_lds_dwordx4 v134, s[66:67]
	s_mov_b32 m0, s78
	s_add_u32 s0, s68, 0x80000
	global_load_lds_dwordx4 v130, s[66:67]
	s_addc_u32 s1, s69, 0
	s_add_i32 m0, s77, 0x14000
	v_mov_b32_e32 v137, 0
	global_load_lds_dwordx4 v132, s[0:1]
	s_add_i32 m0, s77, 0x16000
	v_mov_b32_e32 v133, v137
	global_load_lds_dwordx4 v128, s[0:1]
	s_add_u32 s0, s66, 0x80000
	s_addc_u32 s1, s67, 0
	s_add_i32 s79, s77, 0x4000
	s_mov_b32 m0, s79
	s_add_i32 s80, s77, 0x6000
	global_load_lds_dwordx4 v134, s[0:1]
	s_mov_b32 m0, s80
	v_mov_b32_e32 v129, v137
	global_load_lds_dwordx4 v130, s[0:1]
	v_mov_b32_e32 v135, v137
	v_mov_b32_e32 v131, v137
	s_mov_b32 s81, 0
	v_lshl_add_u64 v[6:7], s[68:69], 0, v[132:133]
	v_lshl_add_u64 v[4:5], s[68:69], 0, v[128:129]
	v_lshl_add_u64 v[2:3], s[66:67], 0, v[134:135]
	s_cmp_lg_u32 s26, 1
	v_lshl_add_u64 v[0:1], s[66:67], 0, v[130:131]
	s_cbranch_scc1 .LBB0_121
	s_barrier
